# v24 plus mid q-up/kv-up: the row-scale sum-of-squares loads are issued at the unit start so their latency overlaps the K loop
# speedup vs baseline: 1.0023x; 1.0013x over previous
.LBB0_1105:
	s_mul_hi_i32 s2, s31, 0x2aaaaaab
	s_lshr_b32 s3, s2, 31
	s_ashr_i32 s34, s2, 1
	v_mov_b32_e32 v40, v208
	s_add_i32 s34, s34, s3
	s_lshl_b32 s38, s34, 7
	v_add_u32_e32 v204, s38, v208
	v_ashrrev_i32_e32 v205, 31, v204
	v_lshlrev_b64 v[204:205], 5, v[204:205]
	v_lshl_add_u64 v[204:205], s[14:15], 0, v[204:205]
	global_load_dwordx4 v[204:207], v[204:205], off
	v_lshlrev_b32_e32 v5, 3, v40
	v_and_b32_e32 v1, 56, v5
	v_ashrrev_i32_e32 v22, 3, v40
	v_mov_b32_e32 v2, v0
	v_mov_b32_e32 v3, v0
	v_lshlrev_b32_e32 v8, 1, v1
	v_mov_b32_e32 v9, v0
	v_add_u32_e32 v4, s38, v22
	v_mov_b32_e32 v1, v0
	v_mov_b64_e32 v[70:71], v[2:3]
	v_lshl_add_u64 v[20:21], s[20:21], 0, v[8:9]
	v_cmp_gt_u32_e64 s[6:7], s50, v4
	v_lshlrev_b32_e32 v24, 10, v4
	v_mov_b64_e32 v[68:69], v[0:1]
	s_and_saveexec_b64 s[2:3], s[6:7]
	s_cbranch_execz .LBB0_1107
	v_mov_b32_e32 v25, v0
	v_lshl_add_u64 v[6:7], v[20:21], 0, v[24:25]
	global_load_dwordx4 v[68:71], v[6:7], off

.LBB0_1143:
	v_lshlrev_b32_e32 v1, 6, v163
	v_lshlrev_b32_e32 v2, 2, v164
	v_lshl_or_b32 v2, v162, 8, v2
	v_lshl_or_b32 v1, v165, 2, v1
	v_mad_u64_u32 v[2:3], s[2:3], v1, s56, v[2:3]
	v_add_u32_e32 v1, 0x400, v2
	ds_write2_b32 v2, v52, v36 offset1:32
	ds_write2_b32 v2, v53, v37 offset0:129 offset1:161
	ds_write2_b32 v1, v54, v38 offset0:2 offset1:34
	ds_write2_b32 v1, v55, v39 offset0:131 offset1:163
	v_add_u32_e32 v1, 0x1000, v2
	ds_write2_b32 v1, v56, v40 offset0:8 offset1:40
	ds_write2_b32 v1, v57, v41 offset0:137 offset1:169
	v_add_u32_e32 v1, 0x1400, v2
	ds_write2_b32 v1, v58, v42 offset0:10 offset1:42
	ds_write2_b32 v1, v59, v43 offset0:139 offset1:171
	v_add_u32_e32 v1, 0x2000, v2
	ds_write2_b32 v1, v60, v44 offset0:16 offset1:48
	ds_write2_b32 v1, v61, v45 offset0:145 offset1:177
	v_add_u32_e32 v1, 0x2400, v2
	ds_write2_b32 v1, v62, v46 offset0:18 offset1:50
	ds_write2_b32 v1, v63, v47 offset0:147 offset1:179
	v_add_u32_e32 v1, 0x3000, v2
	ds_write2_b32 v1, v64, v48 offset0:24 offset1:56
	ds_write2_b32 v1, v65, v49 offset0:153 offset1:185
	v_add_u32_e32 v1, 0x3400, v2
	ds_write2_b32 v1, v66, v50 offset0:26 offset1:58
	ds_write2_b32 v1, v67, v51 offset0:155 offset1:187
	v_add_u32_e32 v1, 0x4000, v2
	ds_write2_b32 v1, v20, v4 offset0:32 offset1:64
	ds_write2_b32 v1, v21, v5 offset0:161 offset1:193
	v_add_u32_e32 v1, 0x4400, v2
	ds_write2_b32 v1, v22, v6 offset0:34 offset1:66
	ds_write2_b32 v1, v23, v7 offset0:163 offset1:195
	v_add_u32_e32 v1, 0x5000, v2
	ds_write2_b32 v1, v24, v8 offset0:40 offset1:72
	ds_write2_b32 v1, v25, v9 offset0:169 offset1:201
	v_add_u32_e32 v1, 0x5400, v2
	ds_write2_b32 v1, v26, v10 offset0:42 offset1:74
	ds_write2_b32 v1, v27, v11 offset0:171 offset1:203
	v_add_u32_e32 v1, 0x6000, v2
	ds_write2_b32 v1, v28, v12 offset0:48 offset1:80
	ds_write2_b32 v1, v29, v13 offset0:177 offset1:209
	v_add_u32_e32 v1, 0x6400, v2
	ds_write2_b32 v1, v30, v14 offset0:50 offset1:82
	ds_write2_b32 v1, v31, v15 offset0:179 offset1:211
	v_add_u32_e32 v1, 0x7000, v2
	ds_write2_b32 v1, v32, v16 offset0:56 offset1:88
	ds_write2_b32 v1, v33, v17 offset0:185 offset1:217
	v_add_u32_e32 v1, 0x7400, v2
	ds_write2_b32 v1, v34, v18 offset0:58 offset1:90
	ds_write2_b32 v1, v35, v19 offset0:187 offset1:219
	v_mov_b32_e32 v1, v208
	s_waitcnt lgkmcnt(0)
	s_barrier
	s_nop 0
	v_cmp_gt_i32_e32 vcc, s35, v1
	s_and_saveexec_b64 s[2:3], vcc
	s_cbranch_execz .LBB0_1145
	v_mov_b32_e32 v1, v208
	s_nop 0
	s_waitcnt vmcnt(0)
	v_add_f32_e32 v1, v204, v205
	v_add_f32_e32 v1, v1, v206
	v_add_f32_e32 v1, v1, v207
	v_fmamk_f32 v1, v1, 0x3b000000, v209
	v_mul_f32_e32 v2, 0x4b800000, v1
	v_cmp_gt_f32_e32 vcc, s52, v1
	s_nop 1
	v_cndmask_b32_e32 v1, v1, v2, vcc
	v_rsq_f32_e32 v1, v1
	v_mov_b32_e32 v2, v208
	v_mul_f32_e32 v3, 0x45800000, v1
	v_cndmask_b32_e32 v1, v1, v3, vcc
	v_lshl_add_u32 v2, v2, 2, v218
	ds_write_b32 v2, v1

.LBB0_1157:
	v_mov_b32_e32 v7, v208
	s_lshl_b32 s2, s31, 3
	s_and_b32 s34, s2, 0xffffff80
	v_add_u32_e32 v204, s34, v208
	v_ashrrev_i32_e32 v205, 31, v204
	v_lshlrev_b64 v[204:205], 5, v[204:205]
	v_lshl_add_u64 v[204:205], s[14:15], 0, v[204:205]
	global_load_dwordx2 v[204:205], v[204:205], off offset:16
	v_lshlrev_b32_e32 v5, 3, v7
	v_and_b32_e32 v1, 56, v5
	v_ashrrev_i32_e32 v14, 3, v7
	v_mov_b32_e32 v2, v0
	v_mov_b32_e32 v3, v0
	v_lshlrev_b32_e32 v8, 1, v1
	v_mov_b32_e32 v9, v0
	v_add_u32_e32 v4, s34, v14
	v_mov_b32_e32 v1, v0
	v_mov_b64_e32 v[70:71], v[2:3]
	v_lshl_add_u64 v[132:133], s[10:11], 0, v[8:9]
	v_cmp_gt_u32_e64 s[2:3], s50, v4
	v_lshlrev_b32_e32 v20, 9, v4
	v_mov_b64_e32 v[68:69], v[0:1]
	s_and_saveexec_b64 s[4:5], s[2:3]
	s_cbranch_execz .LBB0_1159
	v_mov_b32_e32 v21, v0
	v_lshl_add_u64 v[10:11], v[132:133], 0, v[20:21]
	global_load_dwordx4 v[68:71], v[10:11], off

.LBB0_1195:
	v_lshlrev_b32_e32 v1, 6, v169
	v_lshlrev_b32_e32 v2, 2, v170
	v_lshl_or_b32 v2, v168, 8, v2
	v_lshl_or_b32 v1, v171, 2, v1
	v_mad_u64_u32 v[2:3], s[2:3], v1, s56, v[2:3]
	v_add_u32_e32 v1, 0x400, v2
	ds_write2_b32 v2, v52, v36 offset1:32
	ds_write2_b32 v2, v53, v37 offset0:129 offset1:161
	ds_write2_b32 v1, v54, v38 offset0:2 offset1:34
	ds_write2_b32 v1, v55, v39 offset0:131 offset1:163
	v_add_u32_e32 v1, 0x1000, v2
	ds_write2_b32 v1, v56, v40 offset0:8 offset1:40
	ds_write2_b32 v1, v57, v41 offset0:137 offset1:169
	v_add_u32_e32 v1, 0x1400, v2
	ds_write2_b32 v1, v58, v42 offset0:10 offset1:42
	ds_write2_b32 v1, v59, v43 offset0:139 offset1:171
	v_add_u32_e32 v1, 0x2000, v2
	ds_write2_b32 v1, v60, v44 offset0:16 offset1:48
	ds_write2_b32 v1, v61, v45 offset0:145 offset1:177
	v_add_u32_e32 v1, 0x2400, v2
	ds_write2_b32 v1, v62, v46 offset0:18 offset1:50
	ds_write2_b32 v1, v63, v47 offset0:147 offset1:179
	v_add_u32_e32 v1, 0x3000, v2
	ds_write2_b32 v1, v64, v48 offset0:24 offset1:56
	ds_write2_b32 v1, v65, v49 offset0:153 offset1:185
	v_add_u32_e32 v1, 0x3400, v2
	ds_write2_b32 v1, v66, v50 offset0:26 offset1:58
	ds_write2_b32 v1, v67, v51 offset0:155 offset1:187
	v_add_u32_e32 v1, 0x4000, v2
	ds_write2_b32 v1, v20, v4 offset0:32 offset1:64
	ds_write2_b32 v1, v21, v5 offset0:161 offset1:193
	v_add_u32_e32 v1, 0x4400, v2
	ds_write2_b32 v1, v22, v6 offset0:34 offset1:66
	ds_write2_b32 v1, v23, v7 offset0:163 offset1:195
	v_add_u32_e32 v1, 0x5000, v2
	ds_write2_b32 v1, v24, v8 offset0:40 offset1:72
	ds_write2_b32 v1, v25, v9 offset0:169 offset1:201
	v_add_u32_e32 v1, 0x5400, v2
	ds_write2_b32 v1, v26, v10 offset0:42 offset1:74
	ds_write2_b32 v1, v27, v11 offset0:171 offset1:203
	v_add_u32_e32 v1, 0x6000, v2
	ds_write2_b32 v1, v28, v12 offset0:48 offset1:80
	ds_write2_b32 v1, v29, v13 offset0:177 offset1:209
	v_add_u32_e32 v1, 0x6400, v2
	ds_write2_b32 v1, v30, v14 offset0:50 offset1:82
	ds_write2_b32 v1, v31, v15 offset0:179 offset1:211
	v_add_u32_e32 v1, 0x7000, v2
	ds_write2_b32 v1, v32, v16 offset0:56 offset1:88
	ds_write2_b32 v1, v33, v17 offset0:185 offset1:217
	v_add_u32_e32 v1, 0x7400, v2
	ds_write2_b32 v1, v34, v18 offset0:58 offset1:90
	ds_write2_b32 v1, v35, v19 offset0:187 offset1:219
	v_mov_b32_e32 v1, v208
	s_waitcnt lgkmcnt(0)
	s_barrier
	s_nop 0
	v_cmp_gt_i32_e32 vcc, s35, v1
	s_and_saveexec_b64 s[2:3], vcc
	s_cbranch_execz .LBB0_1197
	v_mov_b32_e32 v1, v208
	s_nop 0
	s_waitcnt vmcnt(0)
	v_add_f32_e32 v1, v204, v205
	v_fmamk_f32 v1, v1, 0x3b800000, v209
	v_mul_f32_e32 v2, 0x4b800000, v1
	v_cmp_gt_f32_e32 vcc, s52, v1
	s_nop 1
	v_cndmask_b32_e32 v1, v1, v2, vcc
	v_rsq_f32_e32 v1, v1
	v_mov_b32_e32 v2, v208
	v_mul_f32_e32 v3, 0x45800000, v1
	v_cndmask_b32_e32 v1, v1, v3, vcc
	v_lshl_add_u32 v2, v2, 2, v218
	ds_write_b32 v2, v1
